# EpiGU second form: row statistics computed straight after the K-loop (by the leading wave half while it waits), 4 packed ops + 4 transcendentals per output pair instead of 6+4 (rstd folded into the ex
# speedup vs baseline: 1.0182x; 1.0182x over previous
; #define LAS __attribute__((address_space(3)))
; __device__ __forceinline__ unsigned pk2(float lo, float hi) { return pg8::cvt_pk_bf16(lo, hi); }
; __device__ __forceinline__ float siluf_(float x) { return x * sigmoidf_(x); }
; __device__ __forceinline__ void rows_rstd(LAS unsigned char* sl, int rl0, int fq, float (&rs)[8]) {
;     f32x4 v[8];
; #pragma unroll
;     for (int i = 0; i < 8; ++i) v[i] = *(const LAS f32x4*)(sl + (rl0 + (i >> 2) * 128 + (i & 3) * 16) * 64 + fq * 16);
; #pragma unroll
;     for (int i = 0; i < 8; ++i) { float s = (v[i].x + v[i].y) + (v[i].z + v[i].w); s += __shfl_xor(s, 16); s += __shfl_xor(s, 32); rs[i] = rsqrtf(s * (1.0f / DM) + EPS); }
; }
;     __device__ __forceinline__ void operator()(const f32x4 (&acc)[2][2][4][2], const pg8::Unit& u, int wr, int wc, int fr, int fq) const {
;         const int row0 = u.pm * 256 + wr * 64 + fr, col0 = u.pn * 128 + wc * 32 + 8 * fq;
;         float rs[8]; rows_rstd(sl, wr * 64 + fr, fq, rs);
; #pragma unroll
;         for (int ai = 0; ai < 2; ++ai)
; #pragma unroll
;             for (int m = 0; m < 4; ++m) {
;                 const int row = row0 + ai * 128 + m * 16; const float r = rs[ai * 4 + m];
;                 float h[8];
; #pragma unroll
;                 for (int n = 0; n < 2; ++n)
; #pragma unroll
;                     for (int j = 0; j < 4; ++j) { const float g = acc[ai][0][m][n][j] * r, up = acc[ai][1][m][n][j] * r; h[n * 4 + j] = siluf_(g) * up; }
;                 u32x4 w; w.x = pk2(h[0], h[1]); w.y = pk2(h[2], h[3]); w.z = pk2(h[4], h[5]); w.w = pk2(h[6], h[7]);
;                 *(u32x4*)(H + (size_t)row * FF + col0) = w;
.LBB0_1650:
	v_xor_b32_e32 v130, 16, v175
	v_xor_b32_e32 v131, 32, v175
	ds_read_b128 v[200:203], v198
	ds_read_b128 v[204:207], v198 offset:1024
	ds_read_b128 v[208:211], v198 offset:2048
	ds_read_b128 v[212:215], v198 offset:3072
	ds_read_b128 v[216:219], v198 offset:8192
	ds_read_b128 v[220:223], v198 offset:9216
	ds_read_b128 v[224:227], v198 offset:10240
	ds_read_b128 v[228:231], v198 offset:11264
	v_lshlrev_b32_e32 v130, 2, v130
	v_lshlrev_b32_e32 v131, 2, v131
	v_mov_b32_e32 v134, 0xbfb8aa3b
	v_mov_b32_e32 v135, 0x3a800000
	v_add_u32_e32 v132, s45, v163
	v_mul_u32_u24_e32 v132, 0x1600, v132
	v_lshl_or_b32 v133, s38, 7, v171
	v_lshl_add_u32 v132, v133, 1, v132
	s_waitcnt lgkmcnt(0)
	v_add_f32_e32 v232, v200, v201
	v_add_f32_e32 v233, v204, v205
	v_add_f32_e32 v234, v208, v209
	v_add_f32_e32 v235, v212, v213
	v_add_f32_e32 v236, v216, v217
	v_add_f32_e32 v237, v220, v221
	v_add_f32_e32 v238, v224, v225
	v_add_f32_e32 v239, v228, v229
	v_add_f32_e32 v240, v202, v203
	v_add_f32_e32 v241, v206, v207
	v_add_f32_e32 v242, v210, v211
	v_add_f32_e32 v243, v214, v215
	v_add_f32_e32 v244, v218, v219
	v_add_f32_e32 v245, v222, v223
	v_add_f32_e32 v246, v226, v227
	v_add_f32_e32 v247, v230, v231
	v_add_f32_e32 v232, v232, v240
	v_add_f32_e32 v233, v233, v241
	v_add_f32_e32 v234, v234, v242
	v_add_f32_e32 v235, v235, v243
	v_add_f32_e32 v236, v236, v244
	v_add_f32_e32 v237, v237, v245
	v_add_f32_e32 v238, v238, v246
	v_add_f32_e32 v239, v239, v247
	ds_bpermute_b32 v240, v130, v232
	ds_bpermute_b32 v241, v130, v233
	ds_bpermute_b32 v242, v130, v234
	ds_bpermute_b32 v243, v130, v235
	ds_bpermute_b32 v244, v130, v236
	ds_bpermute_b32 v245, v130, v237
	ds_bpermute_b32 v246, v130, v238
	ds_bpermute_b32 v247, v130, v239
	s_waitcnt lgkmcnt(0)
	v_add_f32_e32 v232, v232, v240
	v_add_f32_e32 v233, v233, v241
	v_add_f32_e32 v234, v234, v242
	v_add_f32_e32 v235, v235, v243
	v_add_f32_e32 v236, v236, v244
	v_add_f32_e32 v237, v237, v245
	v_add_f32_e32 v238, v238, v246
	v_add_f32_e32 v239, v239, v247
	ds_bpermute_b32 v240, v131, v232
	ds_bpermute_b32 v241, v131, v233
	ds_bpermute_b32 v242, v131, v234
	ds_bpermute_b32 v243, v131, v235
	ds_bpermute_b32 v244, v131, v236
	ds_bpermute_b32 v245, v131, v237
	ds_bpermute_b32 v246, v131, v238
	ds_bpermute_b32 v247, v131, v239
	s_waitcnt lgkmcnt(0)
	v_add_f32_e32 v232, v232, v240
	v_add_f32_e32 v233, v233, v241
	v_add_f32_e32 v234, v234, v242
	v_add_f32_e32 v235, v235, v243
	v_add_f32_e32 v236, v236, v244
	v_add_f32_e32 v237, v237, v245
	v_add_f32_e32 v238, v238, v246
	v_add_f32_e32 v239, v239, v247
	v_fmaak_f32 v216, v135, v232, 0x358637bd
	v_fmaak_f32 v218, v135, v233, 0x358637bd
	v_fmaak_f32 v220, v135, v234, 0x358637bd
	v_fmaak_f32 v222, v135, v235, 0x358637bd
	v_fmaak_f32 v224, v135, v236, 0x358637bd
	v_fmaak_f32 v226, v135, v237, 0x358637bd
	v_fmaak_f32 v228, v135, v238, 0x358637bd
	v_fmaak_f32 v230, v135, v239, 0x358637bd
	v_rsq_f32_e32 v200, v216
	v_rsq_f32_e32 v202, v218
	v_rsq_f32_e32 v204, v220
	v_rsq_f32_e32 v206, v222
	v_rsq_f32_e32 v208, v224
	v_rsq_f32_e32 v210, v226
	v_rsq_f32_e32 v212, v228
	v_rsq_f32_e32 v214, v230
	v_mul_f32_e32 v200, v134, v200
	v_mul_f32_e32 v202, v134, v202
	v_mul_f32_e32 v204, v134, v204
	v_mul_f32_e32 v206, v134, v206
	v_mul_f32_e32 v208, v134, v208
	v_mul_f32_e32 v210, v134, v210
	v_mul_f32_e32 v212, v134, v212
	v_mul_f32_e32 v214, v134, v214
	s_and_b64 vcc, exec, s[42:43]
	s_cbranch_vccz .LBB0_1652
	s_barrier
.LBB0_1652:
	v_pk_mul_f32 v[120:121], v[124:125], v[120:121]
	v_pk_mul_f32 v[122:123], v[126:127], v[122:123]
	v_pk_mul_f32 v[112:113], v[116:117], v[112:113]
	v_pk_mul_f32 v[114:115], v[118:119], v[114:115]
	v_pk_mul_f32 v[104:105], v[108:109], v[104:105]
	v_pk_mul_f32 v[106:107], v[110:111], v[106:107]
	v_pk_mul_f32 v[96:97], v[100:101], v[96:97]
	v_pk_mul_f32 v[98:99], v[102:103], v[98:99]
	v_pk_mul_f32 v[124:125], v[124:125], v[200:201] op_sel_hi:[1,0]
	v_pk_mul_f32 v[126:127], v[126:127], v[200:201] op_sel_hi:[1,0]
	v_pk_mul_f32 v[116:117], v[116:117], v[200:201] op_sel_hi:[1,0]
	v_pk_mul_f32 v[118:119], v[118:119], v[200:201] op_sel_hi:[1,0]
	v_pk_mul_f32 v[108:109], v[108:109], v[202:203] op_sel_hi:[1,0]
	v_pk_mul_f32 v[110:111], v[110:111], v[202:203] op_sel_hi:[1,0]
	v_pk_mul_f32 v[100:101], v[100:101], v[202:203] op_sel_hi:[1,0]
	v_pk_mul_f32 v[102:103], v[102:103], v[202:203] op_sel_hi:[1,0]
	v_exp_f32_e32 v124, v124
	v_exp_f32_e32 v125, v125
	v_exp_f32_e32 v126, v126
	v_exp_f32_e32 v127, v127
	v_exp_f32_e32 v116, v116
	v_exp_f32_e32 v117, v117
	v_exp_f32_e32 v118, v118
	v_exp_f32_e32 v119, v119
	v_exp_f32_e32 v108, v108
	v_exp_f32_e32 v109, v109
	v_exp_f32_e32 v110, v110
	v_exp_f32_e32 v111, v111
	v_exp_f32_e32 v100, v100
	v_exp_f32_e32 v101, v101
	v_exp_f32_e32 v102, v102
	v_exp_f32_e32 v103, v103
	v_pk_fma_f32 v[124:125], v[124:125], v[216:217], v[216:217] op_sel_hi:[1,0,0]
	v_pk_fma_f32 v[126:127], v[126:127], v[216:217], v[216:217] op_sel_hi:[1,0,0]
	v_pk_fma_f32 v[116:117], v[116:117], v[216:217], v[216:217] op_sel_hi:[1,0,0]
	v_pk_fma_f32 v[118:119], v[118:119], v[216:217], v[216:217] op_sel_hi:[1,0,0]
	v_pk_fma_f32 v[108:109], v[108:109], v[218:219], v[218:219] op_sel_hi:[1,0,0]
	v_pk_fma_f32 v[110:111], v[110:111], v[218:219], v[218:219] op_sel_hi:[1,0,0]
	v_pk_fma_f32 v[100:101], v[100:101], v[218:219], v[218:219] op_sel_hi:[1,0,0]
	v_pk_fma_f32 v[102:103], v[102:103], v[218:219], v[218:219] op_sel_hi:[1,0,0]
	v_rcp_f32_e32 v124, v124
	v_rcp_f32_e32 v125, v125
	v_rcp_f32_e32 v126, v126
	v_rcp_f32_e32 v127, v127
	v_rcp_f32_e32 v116, v116
	v_rcp_f32_e32 v117, v117
	v_rcp_f32_e32 v118, v118
	v_rcp_f32_e32 v119, v119
	v_rcp_f32_e32 v108, v108
; __device__ __forceinline__ unsigned pk2(float lo, float hi) { return pg8::cvt_pk_bf16(lo, hi); }
; __device__ __forceinline__ float siluf_(float x) { return x * sigmoidf_(x); }
;     __device__ __forceinline__ void operator()(const f32x4 (&acc)[2][2][4][2], const pg8::Unit& u, int wr, int wc, int fr, int fq) const {
;     ...
;         for (int ai = 0; ai < 2; ++ai)
; #pragma unroll
;             for (int m = 0; m < 4; ++m) {
;                 const int row = row0 + ai * 128 + m * 16; const float r = rs[ai * 4 + m];
;                 float h[8];
; #pragma unroll
;                 for (int n = 0; n < 2; ++n)
; #pragma unroll
;                     for (int j = 0; j < 4; ++j) { const float g = acc[ai][0][m][n][j] * r, up = acc[ai][1][m][n][j] * r; h[n * 4 + j] = siluf_(g) * up; }
;                 u32x4 w; w.x = pk2(h[0], h[1]); w.y = pk2(h[2], h[3]); w.z = pk2(h[4], h[5]); w.w = pk2(h[6], h[7]);
;                 *(u32x4*)(H + (size_t)row * FF + col0) = w;
	v_rcp_f32_e32 v109, v109
	v_rcp_f32_e32 v110, v110
	v_rcp_f32_e32 v111, v111
	v_rcp_f32_e32 v100, v100
	v_rcp_f32_e32 v101, v101
	v_rcp_f32_e32 v102, v102
	v_rcp_f32_e32 v103, v103
	v_pk_mul_f32 v[120:121], v[120:121], v[124:125]
	v_pk_mul_f32 v[122:123], v[122:123], v[126:127]
	v_pk_mul_f32 v[112:113], v[112:113], v[116:117]
	v_pk_mul_f32 v[114:115], v[114:115], v[118:119]
	v_pk_mul_f32 v[104:105], v[104:105], v[108:109]
	v_pk_mul_f32 v[106:107], v[106:107], v[110:111]
	v_pk_mul_f32 v[96:97], v[96:97], v[100:101]
	v_pk_mul_f32 v[98:99], v[98:99], v[102:103]
	v_cvt_pk_bf16_f32 v124, v120, v121
	v_cvt_pk_bf16_f32 v125, v122, v123
	v_cvt_pk_bf16_f32 v126, v112, v113
	v_cvt_pk_bf16_f32 v127, v114, v115
	v_cvt_pk_bf16_f32 v108, v104, v105
	v_cvt_pk_bf16_f32 v109, v106, v107
	v_cvt_pk_bf16_f32 v110, v96, v97
	v_cvt_pk_bf16_f32 v111, v98, v99
	v_mov_b32_e32 v136, v132
	global_store_dwordx4 v136, v[124:127], s[8:9] sc1
	v_add_u32_e32 v137, 0x16000, v132
	global_store_dwordx4 v137, v[108:111], s[8:9] sc1
	v_pk_mul_f32 v[88:89], v[92:93], v[88:89]
	v_pk_mul_f32 v[90:91], v[94:95], v[90:91]
	v_pk_mul_f32 v[80:81], v[84:85], v[80:81]
	v_pk_mul_f32 v[82:83], v[86:87], v[82:83]
	v_pk_mul_f32 v[72:73], v[76:77], v[72:73]
	v_pk_mul_f32 v[74:75], v[78:79], v[74:75]
	v_pk_mul_f32 v[64:65], v[68:69], v[64:65]
	v_pk_mul_f32 v[66:67], v[70:71], v[66:67]
	v_pk_mul_f32 v[92:93], v[92:93], v[204:205] op_sel_hi:[1,0]
	v_pk_mul_f32 v[94:95], v[94:95], v[204:205] op_sel_hi:[1,0]
	v_pk_mul_f32 v[84:85], v[84:85], v[204:205] op_sel_hi:[1,0]
	v_pk_mul_f32 v[86:87], v[86:87], v[204:205] op_sel_hi:[1,0]
	v_pk_mul_f32 v[76:77], v[76:77], v[206:207] op_sel_hi:[1,0]
	v_pk_mul_f32 v[78:79], v[78:79], v[206:207] op_sel_hi:[1,0]
	v_pk_mul_f32 v[68:69], v[68:69], v[206:207] op_sel_hi:[1,0]
	v_pk_mul_f32 v[70:71], v[70:71], v[206:207] op_sel_hi:[1,0]
	v_exp_f32_e32 v92, v92
	v_exp_f32_e32 v93, v93
	v_exp_f32_e32 v94, v94
	v_exp_f32_e32 v95, v95
	v_exp_f32_e32 v84, v84
	v_exp_f32_e32 v85, v85
	v_exp_f32_e32 v86, v86
	v_exp_f32_e32 v87, v87
	v_exp_f32_e32 v76, v76
	v_exp_f32_e32 v77, v77
	v_exp_f32_e32 v78, v78
	v_exp_f32_e32 v79, v79
	v_exp_f32_e32 v68, v68
	v_exp_f32_e32 v69, v69
	v_exp_f32_e32 v70, v70
	v_exp_f32_e32 v71, v71
	v_pk_fma_f32 v[92:93], v[92:93], v[220:221], v[220:221] op_sel_hi:[1,0,0]
	v_pk_fma_f32 v[94:95], v[94:95], v[220:221], v[220:221] op_sel_hi:[1,0,0]
	v_pk_fma_f32 v[84:85], v[84:85], v[220:221], v[220:221] op_sel_hi:[1,0,0]
	v_pk_fma_f32 v[86:87], v[86:87], v[220:221], v[220:221] op_sel_hi:[1,0,0]
	v_pk_fma_f32 v[76:77], v[76:77], v[222:223], v[222:223] op_sel_hi:[1,0,0]
	v_pk_fma_f32 v[78:79], v[78:79], v[222:223], v[222:223] op_sel_hi:[1,0,0]
	v_pk_fma_f32 v[68:69], v[68:69], v[222:223], v[222:223] op_sel_hi:[1,0,0]
	v_pk_fma_f32 v[70:71], v[70:71], v[222:223], v[222:223] op_sel_hi:[1,0,0]
	v_rcp_f32_e32 v92, v92
	v_rcp_f32_e32 v93, v93
	v_rcp_f32_e32 v94, v94
	v_rcp_f32_e32 v95, v95
	v_rcp_f32_e32 v84, v84
	v_rcp_f32_e32 v85, v85
	v_rcp_f32_e32 v86, v86
	v_rcp_f32_e32 v87, v87
	v_rcp_f32_e32 v76, v76
	v_rcp_f32_e32 v77, v77
	v_rcp_f32_e32 v78, v78
	v_rcp_f32_e32 v79, v79
	v_rcp_f32_e32 v68, v68
	v_rcp_f32_e32 v69, v69
	v_rcp_f32_e32 v70, v70
	v_rcp_f32_e32 v71, v71
	v_pk_mul_f32 v[88:89], v[88:89], v[92:93]
	v_pk_mul_f32 v[90:91], v[90:91], v[94:95]
	v_pk_mul_f32 v[80:81], v[80:81], v[84:85]
	v_pk_mul_f32 v[82:83], v[82:83], v[86:87]
	v_pk_mul_f32 v[72:73], v[72:73], v[76:77]
	v_pk_mul_f32 v[74:75], v[74:75], v[78:79]
	v_pk_mul_f32 v[64:65], v[64:65], v[68:69]
	v_pk_mul_f32 v[66:67], v[66:67], v[70:71]
	v_cvt_pk_bf16_f32 v92, v88, v89
	v_cvt_pk_bf16_f32 v93, v90, v91
	v_cvt_pk_bf16_f32 v94, v80, v81
	v_cvt_pk_bf16_f32 v95, v82, v83
	v_cvt_pk_bf16_f32 v76, v72, v73
	v_cvt_pk_bf16_f32 v77, v74, v75
	v_cvt_pk_bf16_f32 v78, v64, v65
	v_cvt_pk_bf16_f32 v79, v66, v67
	v_add_u32_e32 v138, 0x2c000, v132
	global_store_dwordx4 v138, v[92:95], s[8:9] sc1
	v_add_u32_e32 v139, 0x42000, v132
	global_store_dwordx4 v139, v[76:79], s[8:9] sc1
	v_pk_mul_f32 v[56:57], v[60:61], v[56:57]
	v_pk_mul_f32 v[58:59], v[62:63], v[58:59]
	v_pk_mul_f32 v[48:49], v[52:53], v[48:49]
	v_pk_mul_f32 v[50:51], v[54:55], v[50:51]
	v_pk_mul_f32 v[40:41], v[44:45], v[40:41]
	v_pk_mul_f32 v[42:43], v[46:47], v[42:43]
	v_pk_mul_f32 v[32:33], v[36:37], v[32:33]
	v_pk_mul_f32 v[34:35], v[38:39], v[34:35]
	v_pk_mul_f32 v[60:61], v[60:61], v[208:209] op_sel_hi:[1,0]
	v_pk_mul_f32 v[62:63], v[62:63], v[208:209] op_sel_hi:[1,0]
	v_pk_mul_f32 v[52:53], v[52:53], v[208:209] op_sel_hi:[1,0]
	v_pk_mul_f32 v[54:55], v[54:55], v[208:209] op_sel_hi:[1,0]
	v_pk_mul_f32 v[44:45], v[44:45], v[210:211] op_sel_hi:[1,0]
	v_pk_mul_f32 v[46:47], v[46:47], v[210:211] op_sel_hi:[1,0]
	v_pk_mul_f32 v[36:37], v[36:37], v[210:211] op_sel_hi:[1,0]
	v_pk_mul_f32 v[38:39], v[38:39], v[210:211] op_sel_hi:[1,0]
	v_exp_f32_e32 v60, v60
	v_exp_f32_e32 v61, v61
	v_exp_f32_e32 v62, v62
	v_exp_f32_e32 v63, v63
	v_exp_f32_e32 v52, v52
	v_exp_f32_e32 v53, v53
	v_exp_f32_e32 v54, v54
	v_exp_f32_e32 v55, v55
; #define PG8_BAR __builtin_amdgcn_s_barrier()
; __device__ __forceinline__ unsigned pk2(float lo, float hi) { return pg8::cvt_pk_bf16(lo, hi); }
; __device__ __forceinline__ float siluf_(float x) { return x * sigmoidf_(x); }
; template <class Epi, class Sched, bool ALIGN_EPI = false, bool SP2 = false>
; __device__ __forceinline__ void gemm_phase(PG8_LAS unsigned char* lds, const Gemm g, const Sched& S, const Epi& E) {
;     ...
;         if constexpr (!Epi::AFTER_DRAIN) { E(acc, cur, wr, wc, fr, fq); S.done(cur); }
;         if (!has_next) break;
;         { typename Epi::Pre pren = E.issue(nxt, wr, wc, fr, fq); E.finish(acc, pren); }
;         cur = nxt; cA = nA; cB = nB; ++ui;
;         if constexpr (ALIGN_EPI) { if (wr == 1) PG8_BAR; }
;     __device__ __forceinline__ void operator()(const f32x4 (&acc)[2][2][4][2], const pg8::Unit& u, int wr, int wc, int fr, int fq) const {
;     ...
;             for (int m = 0; m < 4; ++m) {
;                 const int row = row0 + ai * 128 + m * 16; const float r = rs[ai * 4 + m];
;                 float h[8];
; #pragma unroll
;                 for (int n = 0; n < 2; ++n)
; #pragma unroll
;                     for (int j = 0; j < 4; ++j) { const float g = acc[ai][0][m][n][j] * r, up = acc[ai][1][m][n][j] * r; h[n * 4 + j] = siluf_(g) * up; }
;                 u32x4 w; w.x = pk2(h[0], h[1]); w.y = pk2(h[2], h[3]); w.z = pk2(h[4], h[5]); w.w = pk2(h[6], h[7]);
;                 *(u32x4*)(H + (size_t)row * FF + col0) = w;
	v_exp_f32_e32 v44, v44
	v_exp_f32_e32 v45, v45
	v_exp_f32_e32 v46, v46
	v_exp_f32_e32 v47, v47
	v_exp_f32_e32 v36, v36
	v_exp_f32_e32 v37, v37
	v_exp_f32_e32 v38, v38
	v_exp_f32_e32 v39, v39
	v_pk_fma_f32 v[60:61], v[60:61], v[224:225], v[224:225] op_sel_hi:[1,0,0]
	v_pk_fma_f32 v[62:63], v[62:63], v[224:225], v[224:225] op_sel_hi:[1,0,0]
	v_pk_fma_f32 v[52:53], v[52:53], v[224:225], v[224:225] op_sel_hi:[1,0,0]
	v_pk_fma_f32 v[54:55], v[54:55], v[224:225], v[224:225] op_sel_hi:[1,0,0]
	v_pk_fma_f32 v[44:45], v[44:45], v[226:227], v[226:227] op_sel_hi:[1,0,0]
	v_pk_fma_f32 v[46:47], v[46:47], v[226:227], v[226:227] op_sel_hi:[1,0,0]
	v_pk_fma_f32 v[36:37], v[36:37], v[226:227], v[226:227] op_sel_hi:[1,0,0]
	v_pk_fma_f32 v[38:39], v[38:39], v[226:227], v[226:227] op_sel_hi:[1,0,0]
	v_rcp_f32_e32 v60, v60
	v_rcp_f32_e32 v61, v61
	v_rcp_f32_e32 v62, v62
	v_rcp_f32_e32 v63, v63
	v_rcp_f32_e32 v52, v52
	v_rcp_f32_e32 v53, v53
	v_rcp_f32_e32 v54, v54
	v_rcp_f32_e32 v55, v55
	v_rcp_f32_e32 v44, v44
	v_rcp_f32_e32 v45, v45
	v_rcp_f32_e32 v46, v46
	v_rcp_f32_e32 v47, v47
	v_rcp_f32_e32 v36, v36
	v_rcp_f32_e32 v37, v37
	v_rcp_f32_e32 v38, v38
	v_rcp_f32_e32 v39, v39
	v_pk_mul_f32 v[56:57], v[56:57], v[60:61]
	v_pk_mul_f32 v[58:59], v[58:59], v[62:63]
	v_pk_mul_f32 v[48:49], v[48:49], v[52:53]
	v_pk_mul_f32 v[50:51], v[50:51], v[54:55]
	v_pk_mul_f32 v[40:41], v[40:41], v[44:45]
	v_pk_mul_f32 v[42:43], v[42:43], v[46:47]
	v_pk_mul_f32 v[32:33], v[32:33], v[36:37]
	v_pk_mul_f32 v[34:35], v[34:35], v[38:39]
	v_cvt_pk_bf16_f32 v60, v56, v57
	v_cvt_pk_bf16_f32 v61, v58, v59
	v_cvt_pk_bf16_f32 v62, v48, v49
	v_cvt_pk_bf16_f32 v63, v50, v51
	v_cvt_pk_bf16_f32 v44, v40, v41
	v_cvt_pk_bf16_f32 v45, v42, v43
	v_cvt_pk_bf16_f32 v46, v32, v33
	v_cvt_pk_bf16_f32 v47, v34, v35
	v_add_u32_e32 v140, 0xb0000, v132
	global_store_dwordx4 v140, v[60:63], s[8:9] sc1
	v_add_u32_e32 v141, 0xc6000, v132
	global_store_dwordx4 v141, v[44:47], s[8:9] sc1
	v_pk_mul_f32 v[24:25], v[28:29], v[24:25]
	v_pk_mul_f32 v[26:27], v[30:31], v[26:27]
	v_pk_mul_f32 v[16:17], v[20:21], v[16:17]
	v_pk_mul_f32 v[18:19], v[22:23], v[18:19]
	v_pk_mul_f32 v[8:9], v[12:13], v[8:9]
	v_pk_mul_f32 v[10:11], v[14:15], v[10:11]
	v_pk_mul_f32 v[0:1], v[4:5], v[0:1]
	v_pk_mul_f32 v[2:3], v[6:7], v[2:3]
	v_pk_mul_f32 v[28:29], v[28:29], v[212:213] op_sel_hi:[1,0]
	v_pk_mul_f32 v[30:31], v[30:31], v[212:213] op_sel_hi:[1,0]
	v_pk_mul_f32 v[20:21], v[20:21], v[212:213] op_sel_hi:[1,0]
	v_pk_mul_f32 v[22:23], v[22:23], v[212:213] op_sel_hi:[1,0]
	v_pk_mul_f32 v[12:13], v[12:13], v[214:215] op_sel_hi:[1,0]
	v_pk_mul_f32 v[14:15], v[14:15], v[214:215] op_sel_hi:[1,0]
	v_pk_mul_f32 v[4:5], v[4:5], v[214:215] op_sel_hi:[1,0]
	v_pk_mul_f32 v[6:7], v[6:7], v[214:215] op_sel_hi:[1,0]
	v_exp_f32_e32 v28, v28
	v_exp_f32_e32 v29, v29
	v_exp_f32_e32 v30, v30
	v_exp_f32_e32 v31, v31
	v_exp_f32_e32 v20, v20
	v_exp_f32_e32 v21, v21
	v_exp_f32_e32 v22, v22
	v_exp_f32_e32 v23, v23
	v_exp_f32_e32 v12, v12
	v_exp_f32_e32 v13, v13
	v_exp_f32_e32 v14, v14
	v_exp_f32_e32 v15, v15
	v_exp_f32_e32 v4, v4
	v_exp_f32_e32 v5, v5
	v_exp_f32_e32 v6, v6
	v_exp_f32_e32 v7, v7
	v_pk_fma_f32 v[28:29], v[28:29], v[228:229], v[228:229] op_sel_hi:[1,0,0]
	v_pk_fma_f32 v[30:31], v[30:31], v[228:229], v[228:229] op_sel_hi:[1,0,0]
	v_pk_fma_f32 v[20:21], v[20:21], v[228:229], v[228:229] op_sel_hi:[1,0,0]
	v_pk_fma_f32 v[22:23], v[22:23], v[228:229], v[228:229] op_sel_hi:[1,0,0]
	v_pk_fma_f32 v[12:13], v[12:13], v[230:231], v[230:231] op_sel_hi:[1,0,0]
	v_pk_fma_f32 v[14:15], v[14:15], v[230:231], v[230:231] op_sel_hi:[1,0,0]
	v_pk_fma_f32 v[4:5], v[4:5], v[230:231], v[230:231] op_sel_hi:[1,0,0]
	v_pk_fma_f32 v[6:7], v[6:7], v[230:231], v[230:231] op_sel_hi:[1,0,0]
	v_rcp_f32_e32 v28, v28
	v_rcp_f32_e32 v29, v29
	v_rcp_f32_e32 v30, v30
	v_rcp_f32_e32 v31, v31
	v_rcp_f32_e32 v20, v20
	v_rcp_f32_e32 v21, v21
	v_rcp_f32_e32 v22, v22
	v_rcp_f32_e32 v23, v23
	v_rcp_f32_e32 v12, v12
	v_rcp_f32_e32 v13, v13
	v_rcp_f32_e32 v14, v14
	v_rcp_f32_e32 v15, v15
	v_rcp_f32_e32 v4, v4
	v_rcp_f32_e32 v5, v5
	v_rcp_f32_e32 v6, v6
	v_rcp_f32_e32 v7, v7
	v_pk_mul_f32 v[24:25], v[24:25], v[28:29]
	v_pk_mul_f32 v[26:27], v[26:27], v[30:31]
	v_pk_mul_f32 v[16:17], v[16:17], v[20:21]
	v_pk_mul_f32 v[18:19], v[18:19], v[22:23]
	v_pk_mul_f32 v[8:9], v[8:9], v[12:13]
	v_pk_mul_f32 v[10:11], v[10:11], v[14:15]
	v_pk_mul_f32 v[0:1], v[0:1], v[4:5]
	v_pk_mul_f32 v[2:3], v[2:3], v[6:7]
	v_cvt_pk_bf16_f32 v28, v24, v25
	v_cvt_pk_bf16_f32 v29, v26, v27
	v_cvt_pk_bf16_f32 v30, v16, v17
	v_cvt_pk_bf16_f32 v31, v18, v19
	v_cvt_pk_bf16_f32 v12, v8, v9
	v_cvt_pk_bf16_f32 v13, v10, v11
	v_cvt_pk_bf16_f32 v14, v0, v1
	v_cvt_pk_bf16_f32 v15, v2, v3
	v_add_u32_e32 v142, 0xdc000, v132
	global_store_dwordx4 v142, v[28:31], s[8:9] sc1
	v_add_u32_e32 v143, 0xf2000, v132
	global_store_dwordx4 v143, v[12:15], s[8:9] sc1
	s_andn2_b64 vcc, exec, s[36:37]
	s_mov_b64 s[0:1], -1
	s_cbranch_vccnz .LBB0_1643
	s_andn2_b64 vcc, exec, s[40:41]
	s_cbranch_vccnz .LBB0_1642
	s_barrier
	s_branch .LBB0_1642
